# conv item: 30 halo loads issued together behind one wait instead of 30 serialized load-wait round trips (on top of v2 epilogue batching)
# speedup vs baseline: 1.0226x; 1.0049x over previous
; __device__ __forceinline__ void conv_item(KP p, LAS unsigned char* lds, int l, int tile) {
;     ...
;     const bf16_t* hm = HM + c0;
;     f32x2 w[31];
; #pragma unroll
;     for (int j = 0; j < 31; ++j) w[j] = *(const f32x2*)(p->in[10] + (size_t)(l * 31 + j) * 1024 + c0);
;     const f32x2 cb = *(const f32x2*)(p->in[11] + l * 1024 + c0);
;     f32x2 g[34];
; #pragma unroll
;     for (int i = 0; i < 30; ++i) g[i] = glu_at(hm, tbase - 30 + i);
.LBB0_398:
	s_and_b64 vcc, exec, s[40:41]
	s_cbranch_vccz .LBB0_466
	v_mov_b32_e32 v6, v166
	s_load_dwordx4 s[40:43], s[0:1], 0x50
	v_lshlrev_b32_e32 v2, 1, v6
	v_ashrrev_i32_e32 v3, 31, v2
	v_lshlrev_b64 v[4:5], 2, v[2:3]
	s_movk_i32 s24, 0x4000
	s_waitcnt lgkmcnt(0)
	v_lshl_add_u64 v[8:9], s[40:41], 0, v[4:5]
	v_lshl_add_u64 v[8:9], s[74:75], 2, v[8:9]
	v_add_co_u32_e32 v10, vcc, 0x1000, v8
	s_add_i32 s6, s92, 0xfffffe40
	s_nop 0
	v_addc_co_u32_e32 v11, vcc, 0, v9, vcc
	v_add_co_u32_e32 v12, vcc, s33, v8
	s_lshl_b32 s25, s6, 6
	s_nop 0
	v_addc_co_u32_e32 v13, vcc, 0, v9, vcc
	v_add_co_u32_e32 v14, vcc, 0x3000, v8
	s_lshl_b64 s[44:45], s[14:15], 2
	s_nop 0
	v_addc_co_u32_e32 v15, vcc, 0, v9, vcc
	global_load_dwordx2 v[18:19], v[8:9], off
	global_load_dwordx2 v[20:21], v[10:11], off
	global_load_dwordx2 v[22:23], v[12:13], off
	global_load_dwordx2 v[24:25], v[14:15], off
	v_add_co_u32_e32 v10, vcc, s24, v8
	s_movk_i32 s24, 0x6000
	s_nop 0
	v_addc_co_u32_e32 v11, vcc, 0, v9, vcc
	v_add_co_u32_e32 v12, vcc, 0x5000, v8
	s_add_u32 s40, s42, s44
	s_nop 0
	v_addc_co_u32_e32 v13, vcc, 0, v9, vcc
	v_add_co_u32_e32 v14, vcc, s24, v8
	s_mov_b32 s24, 0x8000
	s_nop 0
	v_addc_co_u32_e32 v15, vcc, 0, v9, vcc
	v_add_co_u32_e32 v16, vcc, 0x7000, v8
	s_addc_u32 s41, s43, s45
	s_nop 0
	v_addc_co_u32_e32 v17, vcc, 0, v9, vcc
	global_load_dwordx2 v[26:27], v[10:11], off
	global_load_dwordx2 v[28:29], v[12:13], off
	global_load_dwordx2 v[30:31], v[14:15], off
	global_load_dwordx2 v[32:33], v[16:17], off
	v_add_co_u32_e32 v10, vcc, s24, v8
	s_mov_b32 s24, 0xa000
	s_nop 0
	v_addc_co_u32_e32 v11, vcc, 0, v9, vcc
	v_add_co_u32_e32 v12, vcc, 0x9000, v8
	v_lshl_add_u64 v[4:5], s[40:41], 0, v[4:5]
	s_nop 0
	v_addc_co_u32_e32 v13, vcc, 0, v9, vcc
	v_add_co_u32_e32 v14, vcc, s24, v8
	s_mov_b32 s24, 0xc000
	s_nop 0
	v_addc_co_u32_e32 v15, vcc, 0, v9, vcc
	v_add_co_u32_e32 v16, vcc, 0xb000, v8
	s_cmp_lg_u32 s6, 0
	s_nop 0
	v_addc_co_u32_e32 v17, vcc, 0, v9, vcc
	global_load_dwordx2 v[34:35], v[10:11], off
	global_load_dwordx2 v[36:37], v[12:13], off
	global_load_dwordx2 v[38:39], v[14:15], off
	global_load_dwordx2 v[40:41], v[16:17], off
	v_add_co_u32_e32 v10, vcc, s24, v8
	s_mov_b32 s24, 0xe000
	s_nop 0
	v_addc_co_u32_e32 v11, vcc, 0, v9, vcc
	v_add_co_u32_e32 v12, vcc, 0xd000, v8
	s_cselect_b64 s[42:43], -1, 0
	s_nop 0
	v_addc_co_u32_e32 v13, vcc, 0, v9, vcc
	v_add_co_u32_e32 v14, vcc, s24, v8
	s_mov_b32 s24, 0x10000
	s_nop 0
	v_addc_co_u32_e32 v15, vcc, 0, v9, vcc
	v_add_co_u32_e32 v16, vcc, 0xf000, v8
	s_cmp_eq_u32 s6, 0
	s_nop 0
	v_addc_co_u32_e32 v17, vcc, 0, v9, vcc
	global_load_dwordx2 v[42:43], v[10:11], off
	global_load_dwordx2 v[44:45], v[12:13], off
	global_load_dwordx2 v[46:47], v[14:15], off
	global_load_dwordx2 v[48:49], v[16:17], off
	v_add_co_u32_e32 v10, vcc, s24, v8
	s_mov_b32 s24, 0x12000
	s_nop 0
	v_addc_co_u32_e32 v11, vcc, 0, v9, vcc
	v_add_co_u32_e32 v12, vcc, 0x11000, v8
	v_lshl_add_u64 v[82:83], v[2:3], 1, s[36:37]
	s_nop 0
	v_addc_co_u32_e32 v13, vcc, 0, v9, vcc
	v_add_co_u32_e32 v14, vcc, s24, v8
	s_mov_b32 s24, 0x14000
	s_nop 0
	v_addc_co_u32_e32 v15, vcc, 0, v9, vcc
	v_add_co_u32_e32 v16, vcc, 0x13000, v8
	s_nop 1
	v_addc_co_u32_e32 v17, vcc, 0, v9, vcc
	global_load_dwordx2 v[50:51], v[10:11], off
	global_load_dwordx2 v[52:53], v[12:13], off
	global_load_dwordx2 v[54:55], v[14:15], off
	global_load_dwordx2 v[56:57], v[16:17], off
	v_add_co_u32_e32 v10, vcc, s24, v8
	s_mov_b32 s24, 0x16000
	s_nop 0
	v_addc_co_u32_e32 v11, vcc, 0, v9, vcc
	v_add_co_u32_e32 v12, vcc, 0x15000, v8
	s_nop 1
	v_addc_co_u32_e32 v13, vcc, 0, v9, vcc
	v_add_co_u32_e32 v14, vcc, s24, v8
	s_mov_b32 s24, 0x18000
	s_nop 0
	v_addc_co_u32_e32 v15, vcc, 0, v9, vcc
	v_add_co_u32_e32 v16, vcc, 0x17000, v8
	s_nop 1
	v_addc_co_u32_e32 v17, vcc, 0, v9, vcc
	global_load_dwordx2 v[58:59], v[10:11], off
	global_load_dwordx2 v[60:61], v[12:13], off
	global_load_dwordx2 v[62:63], v[14:15], off
	global_load_dwordx2 v[64:65], v[16:17], off
	v_add_co_u32_e32 v10, vcc, s24, v8
	s_mov_b32 s24, 0x1a000
	s_nop 0
	v_addc_co_u32_e32 v11, vcc, 0, v9, vcc
	v_add_co_u32_e32 v12, vcc, 0x19000, v8
	s_nop 1
	v_addc_co_u32_e32 v13, vcc, 0, v9, vcc
	v_add_co_u32_e32 v14, vcc, s24, v8
	s_mov_b32 s24, 0x1c000
	s_nop 0
	v_addc_co_u32_e32 v15, vcc, 0, v9, vcc
	v_add_co_u32_e32 v16, vcc, 0x1b000, v8
	s_nop 1
	v_addc_co_u32_e32 v17, vcc, 0, v9, vcc
	global_load_dwordx2 v[66:67], v[10:11], off
	global_load_dwordx2 v[68:69], v[12:13], off
	global_load_dwordx2 v[70:71], v[14:15], off
	global_load_dwordx2 v[72:73], v[16:17], off
	v_add_co_u32_e32 v10, vcc, s24, v8
	s_mov_b32 s24, 0x1e000
	s_nop 0
	v_addc_co_u32_e32 v11, vcc, 0, v9, vcc
	v_add_co_u32_e32 v12, vcc, 0x1d000, v8
	s_nop 1
	v_addc_co_u32_e32 v13, vcc, 0, v9, vcc
	v_add_co_u32_e32 v8, vcc, s24, v8
	v_readfirstlane_b32 s24, v6
	s_nop 0
	v_addc_co_u32_e32 v9, vcc, 0, v9, vcc
	global_load_dwordx2 v[74:75], v[10:11], off
	global_load_dwordx2 v[76:77], v[12:13], off
	global_load_dwordx2 v[78:79], v[8:9], off
	global_load_dwordx2 v[80:81], v[4:5], off
	s_cbranch_scc1 .Lconv_halo_zero
; __device__ __forceinline__ float bflo(unsigned w) { return __uint_as_float(w << 16); }
; __device__ __forceinline__ float bfhi(unsigned w) { return __uint_as_float(w & 0xffff0000u); }
; __device__ __forceinline__ f32x2 glu_at(const bf16_t* hm, int tok) {
;     f32x2 g = (f32x2){0.f, 0.f};
;     if (tok >= 0) { const unsigned va = *(const unsigned*)(hm + (size_t)tok * HMW + C_GLU); g = (f32x2){bflo(va), bfhi(va)}; }
;     return g;
; __device__ __forceinline__ void conv_item(KP p, LAS unsigned char* lds, int l, int tile) {
;     ...
;     f32x2 g[34];
; #pragma unroll
;     for (int i = 0; i < 30; ++i) g[i] = glu_at(hm, tbase - 30 + i);
	s_sub_i32 s40, s25, 30
	v_mad_u64_u32 v[4:5], s[40:41], s40, v171, v[82:83]
	v_add_co_u32_e32 v4, vcc, 0x3000, v4
	s_mov_b64 s[40:41], 0x4200
	v_addc_co_u32_e32 v5, vcc, 0, v5, vcc
	global_load_dword v84, v[4:5], off offset:512
	v_lshl_add_u64 v[4:5], v[4:5], 0, s[40:41]
	global_load_dword v86, v[4:5], off offset:512
	v_lshl_add_u64 v[4:5], v[4:5], 0, s[40:41]
	global_load_dword v88, v[4:5], off offset:512
	v_lshl_add_u64 v[4:5], v[4:5], 0, s[40:41]
	global_load_dword v90, v[4:5], off offset:512
	v_lshl_add_u64 v[4:5], v[4:5], 0, s[40:41]
	global_load_dword v92, v[4:5], off offset:512
	v_lshl_add_u64 v[4:5], v[4:5], 0, s[40:41]
	global_load_dword v94, v[4:5], off offset:512
	v_lshl_add_u64 v[4:5], v[4:5], 0, s[40:41]
	global_load_dword v96, v[4:5], off offset:512
	v_lshl_add_u64 v[4:5], v[4:5], 0, s[40:41]
	global_load_dword v98, v[4:5], off offset:512
	v_lshl_add_u64 v[4:5], v[4:5], 0, s[40:41]
	global_load_dword v100, v[4:5], off offset:512
	v_lshl_add_u64 v[4:5], v[4:5], 0, s[40:41]
	global_load_dword v102, v[4:5], off offset:512
	v_lshl_add_u64 v[4:5], v[4:5], 0, s[40:41]
	global_load_dword v104, v[4:5], off offset:512
	v_lshl_add_u64 v[4:5], v[4:5], 0, s[40:41]
	global_load_dword v106, v[4:5], off offset:512
	v_lshl_add_u64 v[4:5], v[4:5], 0, s[40:41]
	global_load_dword v108, v[4:5], off offset:512
	v_lshl_add_u64 v[4:5], v[4:5], 0, s[40:41]
	global_load_dword v110, v[4:5], off offset:512
	v_lshl_add_u64 v[4:5], v[4:5], 0, s[40:41]
	global_load_dword v112, v[4:5], off offset:512
	v_lshl_add_u64 v[4:5], v[4:5], 0, s[40:41]
	global_load_dword v114, v[4:5], off offset:512
	v_lshl_add_u64 v[4:5], v[4:5], 0, s[40:41]
	global_load_dword v116, v[4:5], off offset:512
	v_lshl_add_u64 v[4:5], v[4:5], 0, s[40:41]
	global_load_dword v118, v[4:5], off offset:512
	v_lshl_add_u64 v[4:5], v[4:5], 0, s[40:41]
	global_load_dword v120, v[4:5], off offset:512
	v_lshl_add_u64 v[4:5], v[4:5], 0, s[40:41]
	global_load_dword v122, v[4:5], off offset:512
	v_lshl_add_u64 v[4:5], v[4:5], 0, s[40:41]
	global_load_dword v124, v[4:5], off offset:512
	v_lshl_add_u64 v[4:5], v[4:5], 0, s[40:41]
	global_load_dword v126, v[4:5], off offset:512
	v_lshl_add_u64 v[4:5], v[4:5], 0, s[40:41]
	global_load_dword v128, v[4:5], off offset:512
	v_lshl_add_u64 v[4:5], v[4:5], 0, s[40:41]
	global_load_dword v130, v[4:5], off offset:512
	v_lshl_add_u64 v[4:5], v[4:5], 0, s[40:41]
	global_load_dword v132, v[4:5], off offset:512
	v_lshl_add_u64 v[4:5], v[4:5], 0, s[40:41]
	global_load_dword v134, v[4:5], off offset:512
	v_lshl_add_u64 v[4:5], v[4:5], 0, s[40:41]
	global_load_dword v136, v[4:5], off offset:512
	v_lshl_add_u64 v[4:5], v[4:5], 0, s[40:41]
	global_load_dword v138, v[4:5], off offset:512
	v_lshl_add_u64 v[4:5], v[4:5], 0, s[40:41]
	global_load_dword v148, v[4:5], off offset:512
	v_lshl_add_u64 v[4:5], v[4:5], 0, s[40:41]
	global_load_dword v150, v[4:5], off offset:512
	s_waitcnt vmcnt(0)
	v_and_b32_e32 v85, 0xffff0000, v84
	v_lshlrev_b32_e32 v84, 16, v84
	v_and_b32_e32 v87, 0xffff0000, v86
	v_lshlrev_b32_e32 v86, 16, v86
	v_and_b32_e32 v89, 0xffff0000, v88
	v_lshlrev_b32_e32 v88, 16, v88
	v_and_b32_e32 v91, 0xffff0000, v90
	v_lshlrev_b32_e32 v90, 16, v90
	v_and_b32_e32 v93, 0xffff0000, v92
	v_lshlrev_b32_e32 v92, 16, v92
	v_and_b32_e32 v95, 0xffff0000, v94
	v_lshlrev_b32_e32 v94, 16, v94
	v_and_b32_e32 v97, 0xffff0000, v96
	v_lshlrev_b32_e32 v96, 16, v96
	v_and_b32_e32 v99, 0xffff0000, v98
	v_lshlrev_b32_e32 v98, 16, v98
	v_and_b32_e32 v101, 0xffff0000, v100
	v_lshlrev_b32_e32 v100, 16, v100
	v_and_b32_e32 v103, 0xffff0000, v102
	v_lshlrev_b32_e32 v102, 16, v102
	v_and_b32_e32 v105, 0xffff0000, v104
	v_lshlrev_b32_e32 v104, 16, v104
	v_and_b32_e32 v107, 0xffff0000, v106
	v_lshlrev_b32_e32 v106, 16, v106
	v_and_b32_e32 v109, 0xffff0000, v108
	v_lshlrev_b32_e32 v108, 16, v108
	v_and_b32_e32 v111, 0xffff0000, v110
	v_lshlrev_b32_e32 v110, 16, v110
	v_and_b32_e32 v113, 0xffff0000, v112
	v_lshlrev_b32_e32 v112, 16, v112
	v_and_b32_e32 v115, 0xffff0000, v114
	v_lshlrev_b32_e32 v114, 16, v114
	v_and_b32_e32 v117, 0xffff0000, v116
	v_lshlrev_b32_e32 v116, 16, v116
	v_and_b32_e32 v119, 0xffff0000, v118
	v_lshlrev_b32_e32 v118, 16, v118
	v_and_b32_e32 v121, 0xffff0000, v120
	v_lshlrev_b32_e32 v120, 16, v120
	v_and_b32_e32 v123, 0xffff0000, v122
	v_lshlrev_b32_e32 v122, 16, v122
	v_and_b32_e32 v125, 0xffff0000, v124
	v_lshlrev_b32_e32 v124, 16, v124
	v_and_b32_e32 v127, 0xffff0000, v126
	v_lshlrev_b32_e32 v126, 16, v126
	v_and_b32_e32 v129, 0xffff0000, v128
	v_lshlrev_b32_e32 v128, 16, v128
	v_and_b32_e32 v131, 0xffff0000, v130
	v_lshlrev_b32_e32 v130, 16, v130
	v_and_b32_e32 v133, 0xffff0000, v132
	v_lshlrev_b32_e32 v132, 16, v132
	v_and_b32_e32 v135, 0xffff0000, v134
	v_lshlrev_b32_e32 v134, 16, v134
	v_and_b32_e32 v137, 0xffff0000, v136
	v_lshlrev_b32_e32 v136, 16, v136
	v_and_b32_e32 v139, 0xffff0000, v138
	v_lshlrev_b32_e32 v138, 16, v138
	v_and_b32_e32 v149, 0xffff0000, v148
	v_lshlrev_b32_e32 v148, 16, v148
	v_and_b32_e32 v151, 0xffff0000, v150
	v_lshlrev_b32_e32 v150, 16, v150
	s_branch .LBB0_460
.Lconv_halo_zero:
	v_mov_b32_e32 v0, v1
	v_mov_b64_e32 v[84:85], v[0:1]
	v_mov_b64_e32 v[86:87], v[0:1]
	v_mov_b64_e32 v[88:89], v[0:1]
	v_mov_b64_e32 v[90:91], v[0:1]
	v_mov_b64_e32 v[92:93], v[0:1]
	v_mov_b64_e32 v[94:95], v[0:1]
	v_mov_b64_e32 v[96:97], v[0:1]
	v_mov_b64_e32 v[98:99], v[0:1]
	v_mov_b64_e32 v[100:101], v[0:1]
	v_mov_b64_e32 v[102:103], v[0:1]
	v_mov_b64_e32 v[104:105], v[0:1]
	v_mov_b64_e32 v[106:107], v[0:1]
	v_mov_b64_e32 v[108:109], v[0:1]
	v_mov_b64_e32 v[110:111], v[0:1]
	v_mov_b64_e32 v[112:113], v[0:1]
	v_mov_b64_e32 v[114:115], v[0:1]
	v_mov_b64_e32 v[116:117], v[0:1]
	v_mov_b64_e32 v[118:119], v[0:1]
	v_mov_b64_e32 v[120:121], v[0:1]
	v_mov_b64_e32 v[122:123], v[0:1]
	v_mov_b64_e32 v[124:125], v[0:1]
	v_mov_b64_e32 v[126:127], v[0:1]
	v_mov_b64_e32 v[128:129], v[0:1]
	v_mov_b64_e32 v[130:131], v[0:1]
	v_mov_b64_e32 v[132:133], v[0:1]
	v_mov_b64_e32 v[134:135], v[0:1]
	v_mov_b64_e32 v[136:137], v[0:1]
	v_mov_b64_e32 v[138:139], v[0:1]
	v_mov_b64_e32 v[148:149], v[0:1]
	v_mov_b64_e32 v[150:151], v[0:1]
